# stagger sleeps doubled (s_sleep 50 for the GEMM phases, 68 for the attention phase) for blocks >= 256
# baseline (speedup 1.0000x reference)
; DI int xcc_id() { return (int)(__builtin_amdgcn_s_getreg((3 << 11) | 20) & 7u); }
; __global__ void __launch_bounds__(256, 2) mega(P p) {
;     ...
;       } else if (k == 6 && EN(7)) {
;         Epi e{};
;         e.xin_ctx = (l == 0) ? p.in[I_CTX] : (const float*)(ws + WS_X);
;         e.xin_lat = (l == 0) ? p.in[I_X] : (const float*)(ws + WS_X) + (size_t)NCTX * DM;
;         e.xout = (float*)(ws + WS_X); e.out = p.out;
;         e.gate_lat = modl + 4096; e.gate_ctx = modl + 6144 + 4096; e.last = (l == NL - 1);
;         const bf16_t* Bt = (const bf16_t*)(ws + WS_WTOUT) + (size_t)l * DM * LDP;
;         const int g0 = xcc_id();
;         for (int gi = 0; gi < 8; ++gi) {
;           const int g = (g0 + gi) & 7;
;           unsigned* gctr = ctrs + 128 + ph2 * 8 + g;
;           int tm, tn;
;           const int mt_n = e.last ? 64 : 66, mt_0 = e.last ? 2 : 0;
;           int i = next_item(gctr, &s_item);
.LBB0_10:
	v_readlane_b32 s0, v255, 11
	s_cmp_lt_i32 s0, 5
	s_mov_b64 s[0:1], -1
	s_cbranch_scc1 .LBB0_50
	v_readlane_b32 s0, v255, 11
	s_cmp_lt_i32 s0, 6
	s_mov_b64 s[0:1], -1
	s_cbranch_scc1 .LBB0_38
	v_readlane_b32 s0, v255, 11
	s_cmp_eq_u32 s0, 6
	v_readlane_b32 s0, v255, 2
	s_mov_b32 s16, s0
	v_readlane_b32 s24, v255, 3
	s_cbranch_scc0 .LBB0_37
	v_readlane_b32 s0, v252, 0
	s_nop 0
	s_cmpk_lt_u32 s0, 0x100
	s_cbranch_scc1 .Lstag_k6
	s_sleep 50

; DI int xcc_id() { return (int)(__builtin_amdgcn_s_getreg((3 << 11) | 20) & 7u); }
; __global__ void __launch_bounds__(256, 2) mega(P p) {
;     ...
;       } else if (k == 4 && EN(5)) {
;         const int g0 = xcc_id();
;         for (int gi = 0; gi < 8; ++gi) {
;         const int g = (g0 + gi) & 7;
;         unsigned* gctr = ctrs + 128 + ph2 * 8 + g;
;         const int tot = (g < 4) ? 84 : 24 + 128;
;         for (int iq = next_item(gctr, &s_item); iq < tot; iq = next_item(gctr, &s_item)) {
.LBB0_50:
	s_andn2_b64 vcc, exec, s[0:1]
	s_cbranch_vccnz .LBB0_289
	v_readlane_b32 s0, v255, 11
	s_cmp_gt_i32 s0, 3
	s_mov_b64 s[0:1], -1
	s_cbranch_scc0 .LBB0_172
	v_readlane_b32 s0, v252, 0
	s_nop 0
	s_cmpk_lt_u32 s0, 0x100
	s_cbranch_scc1 .Lstag_k4
	s_sleep 68

; DI int xcc_id() { return (int)(__builtin_amdgcn_s_getreg((3 << 11) | 20) & 7u); }
; __global__ void __launch_bounds__(256, 2) mega(P p) {
;     ...
;       } else if (k == 1 && EN(2)) {
;         Epi e{}; e.cb = U; e.cf = (float*)(ws + WS_AB);
;         const bf16_t* Bt = (const bf16_t*)(ws + WS_WTIN) + (size_t)l * INP * LDP;
;         const int g0 = xcc_id();
;         for (int gi = 0; gi < 8; ++gi) {
;           const int g = (g0 + gi) & 7;
;           unsigned* gctr = ctrs + 128 + ph2 * 8 + g;
;           int tm, tn;
;           int i = next_item(gctr, &s_item);
.LBB0_382:
	s_andn2_b64 vcc, exec, s[0:1]
	v_readlane_b32 s0, v255, 0
	s_mov_b32 s2, s0
	v_readlane_b32 s0, v255, 1
	s_mov_b32 s10, s0
	s_cbranch_vccnz .LBB0_472
	v_readlane_b32 s0, v252, 0
	s_nop 0
	s_cmpk_lt_u32 s0, 0x100
	s_cbranch_scc1 .Lstag_k1
	s_sleep 50
